# GEMM phase prologues: K-tile 1 staging issued together with K-tile 0 (one exposed latency instead of two); first wait vmcnt(8)
# baseline (speedup 1.0000x reference)
.LBB0_34:
	v_readlane_b32 s18, v255, 9
	v_readlane_b32 s19, v255, 10
	s_add_u32 s4, s18, 0x5f00000
	s_addc_u32 s5, s19, 0
	s_add_u32 s10, s18, 0x6300000
	s_addc_u32 s11, s19, 0
	s_add_u32 s18, s18, 0x5600000
	v_lshrrev_b32_e32 v11, 1, v231
	v_readlane_b32 s42, v254, 9
	s_addc_u32 s19, s19, 0
	v_and_b32_e32 v11, 24, v11
	s_lshl_b32 s21, s21, 5
	v_readlane_b32 s43, v254, 10
	v_and_b32_e32 v97, 15, v231
	v_lshlrev_b32_e32 v16, 1, v11
	v_lshlrev_b32_e32 v17, 2, v231
	s_and_b32 s30, s21, 0x60
	s_add_i32 m0, s8, 0x18000
	v_lshl_add_u64 v[2:3], v[2:3], 0, s[34:35]
	v_lshl_add_u64 v[12:13], s[42:43], 0, v[208:209]
	s_lshl_b32 s25, s22, 6
	v_lshl_or_b32 v16, v97, 6, v16
	s_lshl_b32 s22, s22, 13
	v_and_b32_e32 v17, 32, v17
	s_lshl_b32 s21, s30, 7
	global_load_lds_dwordx4 v[2:3], off
	v_lshl_add_u64 v[2:3], v[4:5], 0, s[34:35]
	s_add_i32 m0, s8, 0x1a000
	s_add_i32 s28, s8, 0x8000
	s_add_i32 s29, s8, 0xa000
	v_lshl_add_u64 v[14:15], s[42:43], 0, v[94:95]
	v_bitop3_b32 v18, v16, s22, v17 bitop3:0xde
	global_load_lds_dwordx4 v[2:3], off
	v_lshl_add_u64 v[2:3], v[12:13], 0, s[34:35]
	s_mov_b32 m0, s28
	s_add_u32 s22, s44, 0x40080
	global_load_lds_dwordx4 v[2:3], off
	v_lshl_add_u64 v[2:3], v[14:15], 0, s[34:35]
	s_mov_b32 m0, s29
	s_addc_u32 s23, s45, 0
	global_load_lds_dwordx4 v[2:3], off
	s_add_i32 m0, s8, 0x1c000
	v_lshl_add_u64 v[2:3], s[22:23], 0, v[208:209]
	global_load_lds_dwordx4 v[2:3], off
	v_lshl_add_u64 v[2:3], s[22:23], 0, v[94:95]
	s_add_i32 m0, s8, 0x1e000
	v_readlane_b32 s22, v255, 15
	global_load_lds_dwordx4 v[2:3], off
	s_waitcnt vmcnt(8)
	s_barrier
	v_lshlrev_b32_e32 v2, 14, v8
	v_and_b32_e32 v2, 0xffff8000, v2
	v_lshl_add_u32 v2, v9, 11, v2
	v_and_b32_e32 v3, 1, v8
	v_lshl_or_b32 v2, v3, 6, v2
	v_lshl_add_u32 v210, v10, 1, v2
	v_lshlrev_b32_e32 v2, 14, v0
	v_and_b32_e32 v2, 0xffff8000, v2
	s_waitcnt vmcnt(6)
	s_cmpk_lt_u32 s20, 0x100
	v_readlane_b32 s23, v255, 16
	v_lshl_add_u32 v2, v6, 11, v2
	v_and_b32_e32 v0, 1, v0
	v_bitop3_b32 v233, s21, v16, v17 bitop3:0xf6
	s_cselect_b64 s[20:21], -1, 0
	s_ashr_i32 s33, s22, 31
	v_lshl_or_b32 v0, v0, 6, v2
	v_readlane_b32 s22, v254, 1
	v_or_b32_e32 v232, s25, v97
	v_or_b32_e32 v234, s30, v11
	v_mov_b32_e32 v211, v1
	v_lshl_add_u32 v212, v7, 1, v0
	v_mov_b32_e32 v213, v1
	s_mov_b32 s50, 0
	v_add_u32_e32 v235, 0, v18
	v_readlane_b32 s46, v254, 0
	s_mov_b32 s47, s22
	s_barrier
	v_readlane_b32 s23, v254, 2
	s_branch .LBB0_37

.LBB0_397:
	v_readlane_b32 s56, v255, 9
	v_readlane_b32 s57, v255, 10
	s_add_u32 s4, s56, 0x5400000
	s_addc_u32 s5, s57, 0
	s_add_u32 s10, s56, 0x5600000
	s_addc_u32 s11, s57, 0
	s_add_u32 s18, s56, 0x5800000
	s_addc_u32 s19, s57, 0
	s_add_u32 s20, s56, 0x5a00000
	s_addc_u32 s21, s57, 0
	s_add_u32 s22, s56, 0x5c00000
	s_addc_u32 s23, s57, 0
	s_add_u32 s38, s56, 0x5c80000
	s_addc_u32 s39, s57, 0
	s_add_u32 s40, s56, 0x5d00000
	s_addc_u32 s41, s57, 0
	s_add_u32 s42, s56, 0x5d80000
	s_addc_u32 s43, s57, 0
	s_add_u32 s44, s56, 0x5e00000
	s_addc_u32 s45, s57, 0
	s_add_u32 s46, s56, 0x5e80000
	s_addc_u32 s47, s57, 0
	s_add_u32 s48, s56, 0x5f00000
	s_addc_u32 s49, s57, 0
	s_add_u32 s50, s56, 0x6300000
	s_addc_u32 s51, s57, 0
	v_bfe_u32 v16, v231, 4, 2
	s_add_u32 s52, s56, 0x6700000
	v_and_b32_e32 v97, 15, v231
	v_lshlrev_b32_e32 v0, 4, v16
	v_lshlrev_b32_e32 v18, 2, v231
	s_addc_u32 s53, s57, 0
	s_and_b32 s37, s36, 3
	s_lshl_b32 s28, s29, 6
	v_lshl_or_b32 v17, v97, 6, v0
	s_lshl_b32 s29, s29, 13
	v_and_b32_e32 v18, 32, v18
	s_add_i32 m0, s9, 0x18000
	v_lshl_add_u64 v[8:9], v[8:9], 0, s[34:35]
	v_bitop3_b32 v19, v17, s29, v18 bitop3:0xde
	s_lshl_b32 s29, s37, 5
	s_lshl_b32 s30, s37, 12
	global_load_lds_dwordx4 v[8:9], off
	v_lshl_add_u64 v[6:7], v[6:7], 0, s[34:35]
	s_add_i32 m0, s9, 0x1a000
	s_add_i32 s33, s9, 0x8000
	s_add_i32 s80, s9, 0xa000
	v_bitop3_b32 v169, s30, v17, v18 bitop3:0xf6
	global_load_lds_dwordx4 v[6:7], off
	v_lshl_add_u64 v[2:3], v[2:3], 0, s[34:35]
	s_mov_b32 m0, s33
	s_add_u32 s30, s64, 0x40080
	global_load_lds_dwordx4 v[2:3], off
	v_lshl_add_u64 v[2:3], v[4:5], 0, s[34:35]
	s_mov_b32 m0, s80
	s_addc_u32 s31, s65, 0
	global_load_lds_dwordx4 v[2:3], off
	s_add_i32 m0, s9, 0x1c000
	v_lshl_add_u64 v[2:3], s[30:31], 0, v[166:167]
	global_load_lds_dwordx4 v[2:3], off
	v_lshl_add_u64 v[2:3], s[30:31], 0, v[94:95]
	s_add_i32 m0, s9, 0x1e000
	s_cmpk_lt_u32 s6, 0x100
	global_load_lds_dwordx4 v[2:3], off
	s_waitcnt vmcnt(8)
	s_barrier
	s_cselect_b64 s[30:31], -1, 0
	s_bfe_u32 s81, s36, 0x10001
	s_bfe_u32 s6, s6, 0x10006
	s_cmp_eq_u32 s37, 0
	v_lshlrev_b32_e32 v2, 14, v16
	v_readlane_b32 s36, v255, 15
	s_cselect_b64 s[54:55], -1, 0
	v_lshl_or_b32 v172, s6, 17, v2
	s_lshl_b32 s83, s6, 5
	s_lshl_b32 s84, s6, 4
	s_ashr_i32 s85, s36, 31
	s_lshl_b32 s6, s6, 6
	v_readlane_b32 s37, v255, 16
	s_add_u32 s36, s56, s6
	s_addc_u32 s37, s57, 0
	v_lshl_add_u64 v[2:3], s[36:37], 0, v[0:1]
	s_mov_b64 s[36:37], 0x100000
	v_lshlrev_b32_e32 v0, 14, v10
	v_lshl_add_u64 v[174:175], v[2:3], 0, s[36:37]
	s_mov_b64 s[36:37], 0x140000
	v_and_b32_e32 v0, 0xffff8000, v0
	v_lshl_add_u64 v[176:177], v[2:3], 0, s[36:37]
	v_lshl_add_u32 v0, v11, 11, v0
	v_and_b32_e32 v2, 1, v10
	v_lshl_or_b32 v0, v2, 6, v0
	v_lshl_add_u32 v178, v12, 1, v0
	v_lshlrev_b32_e32 v0, 14, v13
	v_and_b32_e32 v0, 0xffff8000, v0
	s_waitcnt vmcnt(6)
	v_lshl_add_u32 v0, v14, 11, v0
	v_and_b32_e32 v2, 1, v13
	v_lshl_or_b32 v0, v2, 6, v0
	v_readlane_b32 s36, v254, 25
	v_lshlrev_b32_e32 v168, 3, v16
	s_mov_b32 s82, 0
	v_lshlrev_b32_e32 v170, 2, v16
	v_mov_b32_e32 v173, v1
	v_mov_b32_e32 v179, v1
	v_lshl_add_u32 v180, v15, 1, v0
	v_mov_b32_e32 v181, v1
	v_add_u32_e32 v171, 0, v19
	v_readlane_b32 s78, v254, 18
	s_mov_b32 s6, s36
	s_barrier
	v_readlane_b32 s37, v254, 26
	s_branch .LBB0_400

.LBB0_514:
	s_add_i32 m0, s28, 0x18000
	v_lshl_add_u64 v[2:3], v[2:3], 0, s[34:35]
	global_load_lds_dwordx4 v[2:3], off
	v_lshl_add_u64 v[2:3], v[4:5], 0, s[34:35]
	s_add_i32 m0, s28, 0x1a000
	s_add_i32 s43, s28, 0x8000
	global_load_lds_dwordx4 v[2:3], off
	v_lshl_add_u64 v[2:3], v[10:11], 0, s[34:35]
	s_mov_b32 m0, s43
	s_add_i32 s44, s28, 0xa000
	global_load_lds_dwordx4 v[2:3], off
	v_lshl_add_u64 v[2:3], v[12:13], 0, s[34:35]
	s_mov_b32 m0, s44
	v_cndmask_b32_e64 v134, 0.5, 1.0, s[0:1]
	global_load_lds_dwordx4 v[2:3], off
	s_add_i32 m0, s28, 0x1c000
	v_lshl_add_u64 v[2:3], v[6:7], 0, s[34:35]
	global_load_lds_dwordx4 v[2:3], off
	v_lshl_add_u64 v[2:3], v[8:9], 0, s[34:35]
	s_add_i32 m0, s28, 0x1e000
	v_lshlrev_b32_e32 v6, 2, v231
	global_load_lds_dwordx4 v[2:3], off
	s_waitcnt vmcnt(8)
	s_barrier
	v_bfe_u32 v2, v231, 4, 2
	v_and_b32_e32 v3, 15, v231
	v_lshlrev_b32_e32 v4, 4, v2
	s_and_b32 s0, s19, 3
	s_lshr_b32 s45, s10, 6
	v_lshl_or_b32 v5, v3, 6, v4
	s_lshl_b32 s1, s11, 13
	v_and_b32_e32 v6, 32, v6
	v_bitop3_b32 v7, v5, s1, v6 bitop3:0xde
	s_lshl_b32 s1, s0, 12
	s_add_i32 s46, s45, -2
	s_cmpk_lt_u32 s18, 0x100
	v_lshl_or_b32 v97, s11, 6, v3
	v_bitop3_b32 v232, s1, v5, v6 bitop3:0xf6
	s_cselect_b64 s[10:11], -1, 0
	v_lshlrev_b32_e32 v5, 2, v2
	s_and_b32 s1, s18, 0xffffff00
	s_lshl_b32 s18, s0, 6
	v_lshl_or_b32 v233, s0, 5, v5
	v_cmp_eq_u32_e64 s[36:37], 0, v2
	s_or_b32 s1, s18, s1
	s_lshl_b32 s0, s0, 2
	v_add_u32_e32 v2, v14, v15
	v_or3_b32 v234, s1, v4, v3
	s_add_i32 s0, s0, 0
	v_add_lshl_u32 v2, v2, v16, 1
	v_mov_b32_e32 v3, v1
	s_add_i32 s0, s0, 0x20400
	v_lshl_add_u64 v[136:137], s[6:7], 0, v[2:3]
	v_add_u32_e32 v2, v17, v18
	s_waitcnt vmcnt(6)
	s_movk_i32 s1, 0x100
	v_lshlrev_b32_e32 v4, 4, v234
	v_readlane_b32 s18, v255, 15
	v_lshl_add_u32 v235, v97, 4, s0
	v_add_lshl_u32 v2, v2, v19, 1
	v_readlane_b32 s0, v254, 0
	v_cmp_gt_i32_e64 s[38:39], s1, v234
	v_readlane_b32 s19, v255, 16
	s_ashr_i32 s48, s18, 31
	v_lshl_add_u64 v[138:139], s[6:7], 0, v[2:3]
	v_add_u32_e32 v2, 0, v4
	s_mov_b32 s18, s0
	v_readlane_b32 s0, v254, 1
	s_mov_b32 s47, 0
	v_mov_b32_e32 v135, v134
	v_add_u32_e32 v236, 0, v7
	v_add_u32_e32 v237, 0x20400, v2
	s_mov_b32 s19, s0
	s_barrier
	v_readlane_b32 s1, v254, 2
	s_branch .LBB0_517

.LBB0_559:
	v_readlane_b32 s4, v255, 9
	v_readlane_b32 s5, v255, 10
	s_add_u32 s4, s4, 0x5400000
	v_lshrrev_b32_e32 v15, 1, v231
	s_addc_u32 s5, s5, 0
	v_and_b32_e32 v15, 24, v15
	s_lshl_b32 s11, s11, 5
	v_and_b32_e32 v97, 15, v231
	v_lshlrev_b32_e32 v16, 1, v15
	v_lshlrev_b32_e32 v17, 2, v231
	s_and_b32 s20, s11, 0x60
	s_add_i32 m0, s8, 0x18000
	v_lshl_add_u64 v[8:9], v[8:9], 0, s[34:35]
	s_lshl_b32 s25, s18, 6
	v_lshl_or_b32 v16, v97, 6, v16
	s_lshl_b32 s18, s18, 13
	v_and_b32_e32 v17, 32, v17
	s_lshl_b32 s11, s20, 7
	global_load_lds_dwordx4 v[8:9], off
	v_lshl_add_u64 v[6:7], v[6:7], 0, s[34:35]
	s_add_i32 m0, s8, 0x1a000
	s_add_i32 s28, s8, 0x8000
	s_add_i32 s29, s8, 0xa000
	v_bitop3_b32 v18, v16, s18, v17 bitop3:0xde
	global_load_lds_dwordx4 v[6:7], off
	v_lshl_add_u64 v[2:3], v[2:3], 0, s[34:35]
	s_mov_b32 m0, s28
	s_add_u32 s18, s38, 0x40080
	global_load_lds_dwordx4 v[2:3], off
	v_lshl_add_u64 v[2:3], v[4:5], 0, s[34:35]
	s_mov_b32 m0, s29
	s_addc_u32 s19, s39, 0
	global_load_lds_dwordx4 v[2:3], off
	s_add_i32 m0, s8, 0x1c000
	v_lshl_add_u64 v[2:3], s[18:19], 0, v[134:135]
	global_load_lds_dwordx4 v[2:3], off
	v_lshl_add_u64 v[2:3], s[18:19], 0, v[94:95]
	s_add_i32 m0, s8, 0x1e000
	v_readlane_b32 s18, v255, 15
	global_load_lds_dwordx4 v[2:3], off
	s_waitcnt vmcnt(8)
	s_barrier
	v_lshlrev_b32_e32 v2, 14, v0
	v_and_b32_e32 v2, 0xffff8000, v2
	v_lshl_add_u32 v2, v10, 11, v2
	v_and_b32_e32 v0, 1, v0
	v_lshl_or_b32 v0, v0, 6, v2
	v_lshl_add_u32 v136, v11, 1, v0
	v_lshlrev_b32_e32 v0, 14, v12
	v_and_b32_e32 v0, 0xffff8000, v0
	s_waitcnt vmcnt(6)
	s_cmpk_lt_u32 s10, 0x100
	v_readlane_b32 s19, v255, 16
	v_lshl_add_u32 v0, v13, 11, v0
	v_and_b32_e32 v2, 1, v12
	v_bitop3_b32 v141, s11, v16, v17 bitop3:0xf6
	s_cselect_b64 s[10:11], -1, 0
	s_ashr_i32 s33, s18, 31
	v_lshl_or_b32 v0, v2, 6, v0
	v_readlane_b32 s18, v254, 21
	v_or_b32_e32 v143, s20, v15
	v_mov_b32_e32 v137, v1
	v_lshl_add_u32 v138, v14, 1, v0
	v_mov_b32_e32 v139, v1
	s_mov_b32 s44, 0
	v_add_u32_e32 v145, 0, v18
	v_readlane_b32 s45, v254, 15
	s_mov_b32 s46, s18
	s_barrier
	v_readlane_b32 s19, v254, 22
	s_branch .LBB0_562
